# plus: grid barrier - followers poll the top generation word directly, acquire L1 invalidate issued at arrival instead of after release
# speedup vs baseline: 1.0161x; 1.0161x over previous
.LBB0_13:
	s_or_b64 exec, exec, s[6:7]
.LBB0_14:
	s_or_b64 exec, exec, s[0:1]
	s_waitcnt lgkmcnt(0)
	s_barrier

.LBB0_966:
	s_or_b64 exec, exec, s[8:9]
	buffer_inv sc1
	v_cvt_f32_u32_e32 v5, v3
	s_waitcnt vmcnt(1)
	v_readfirstlane_b32 s6, v4
	v_sub_u32_e32 v4, 0, v3
	v_rcp_iflag_f32_e32 v5, v5
	v_add_u32_e32 v6, s6, v0
	v_mul_f32_e32 v5, 0x4f7ffffe, v5
	v_cvt_u32_f32_e32 v5, v5
	v_mul_lo_u32 v0, v4, v5
	v_mul_hi_u32 v0, v5, v0
	v_add_u32_e32 v0, v5, v0
	v_mul_hi_u32 v0, v6, v0
	v_mul_lo_u32 v4, v0, v3
	v_sub_u32_e32 v4, v6, v4
	v_add_u32_e32 v5, 1, v0
	v_cmp_ge_u32_e32 vcc, v4, v3
	s_nop 1
	v_cndmask_b32_e32 v0, v0, v5, vcc
	v_sub_u32_e32 v5, v4, v3
	v_cndmask_b32_e32 v4, v4, v5, vcc
	v_add_u32_e32 v5, 1, v0
	v_cmp_ge_u32_e32 vcc, v4, v3
	v_add_u32_e32 v4, 1, v6
	s_nop 0
	v_cndmask_b32_e32 v0, v0, v5, vcc
	v_mul_lo_u32 v5, v3, v0
	v_add_u32_e32 v3, v5, v3
	v_cmp_ne_u32_e32 vcc, v4, v3
	s_and_saveexec_b64 s[6:7], vcc
	s_xor_b64 s[6:7], exec, s[6:7]
	s_cbranch_execz .LBB0_985
	s_waitcnt lgkmcnt(0)
	s_add_u32 s10, s2, 0x3500
	s_addc_u32 s11, s3, 0
	global_load_dword v2, v1, s[10:11] sc1
	s_waitcnt vmcnt(0)
	v_cmp_eq_u32_e32 vcc, v2, v0
	s_and_saveexec_b64 s[8:9], vcc
	s_cbranch_execz .LBB0_984
	s_mov_b32 s22, 1
	s_mov_b64 s[12:13], 0
	s_branch .LBB0_970

.LBB0_984:
	s_or_b64 exec, exec, s[8:9]
	s_waitcnt vmcnt(0)
.LBB0_985:
	s_andn2_saveexec_b64 s[6:7], s[6:7]
	s_cbranch_execz .LBB0_14
	s_mov_b64 s[6:7], exec
	buffer_wbl2 sc1
	s_waitcnt lgkmcnt(0)
	s_waitcnt vmcnt(0)
	v_mbcnt_lo_u32_b32 v0, s6, 0
	v_mbcnt_hi_u32_b32 v0, s7, v0
	v_cmp_eq_u32_e32 vcc, 0, v0
	s_and_saveexec_b64 s[8:9], vcc
	s_cbranch_execz .LBB0_988
	s_bcnt1_i32_b64 s6, s[6:7]
	v_mov_b32_e32 v3, s6
	v_mov_b32_e32 v4, 0x3000
	global_atomic_add v3, v4, v3, s[2:3] offset:1024 sc0

.LBB0_1002:
	s_or_b64 exec, exec, s[2:3]
	s_mov_b64 s[2:3], exec
	v_mbcnt_lo_u32_b32 v0, s2, 0
	v_mbcnt_hi_u32_b32 v0, s3, v0
	v_cmp_eq_u32_e32 vcc, 0, v0
	s_and_saveexec_b64 s[6:7], vcc
	s_cbranch_execz .LBB0_13
	s_bcnt1_i32_b64 s2, s[2:3]
	v_mov_b32_e32 v0, s2
	s_branch .LBB0_13
